# v21c: v18 + hg2 backward z tile requested behind first barrier (drained with the state tile), rt2 second-block gains early, hg1 head leaves 4 stores in flight
# speedup vs baseline: 1.0001x; 1.0001x over previous
; template <int NC> __device__ __forceinline__ void raw_load(const Ctx& X, const bf16* H, size_t m0, int col, RawRegs<NC>& R) {
; #pragma unroll
;     for (int p = 0; p < NC / 64; ++p) { const int idx = X.tid + NTHR * p, r = idx / (NC / 8), c8 = idx % (NC / 8); R.w[p] = *(const v4u*)hptr(H, m0 + r, col + 8 * c8); }
; }
; template <int NC> __device__ __forceinline__ void raw_store(const Ctx& X, lptr dst, const RawRegs<NC>& R) {
; #pragma unroll
;     for (int p = 0; p < NC / 64; ++p) { const int idx = X.tid + NTHR * p; *(LAS v4u*)(dst + idx * 16) = R.w[p]; }
; }
; __device__ __forceinline__ void vt_store(const Ctx& X, lptr VT, const RawRegs<128>& R) {
; #pragma unroll
;     for (int p = 0; p < 2; ++p) { const int idx = X.tid + NTHR * p, r = idx >> 4, c8 = idx & 15; const v4u w = R.w[p];
;         LAS unsigned short* d = (LAS unsigned short*)(VT + (8 * c8) * 144 + (r ^ (8 * (c8 & 7))) * 2);
;         d[0] = (unsigned short)w.x; d[72] = (unsigned short)(w.x >> 16); d[144] = (unsigned short)w.y; d[216] = (unsigned short)(w.y >> 16);
;         d[288] = (unsigned short)w.z; d[360] = (unsigned short)(w.z >> 16); d[432] = (unsigned short)w.w; d[504] = (unsigned short)(w.w >> 16); }
; template <bool RET> __device__ __forceinline__ void loc_load(const Ctx& X, const bf16* H, int r, LocRegs<RET>& R) {
;     const int b = r / 768, head = (r / 128) % 6, n = r % 128; const size_t m0 = (size_t)(b * SEQ + n * CH);
;     raw_load<128>(X, H, m0, (RET ? C_RV : C_HGV) + head * 128, R.rv);
;     if (!RET) { raw_load<128>(X, H, m0, C_ZF + head * 128, R.rzf); raw_load<128>(X, H, m0, C_ZB + head * 128, R.rzb); }
;     else { raw_load<64>(X, H, m0, C_RQ + head * 64, R.rq); raw_load<64>(X, H, m0, C_RK + head * 64, R.rk);
;         const float* rc = (const float*)(X.ws + WS_ROPE) + (size_t)n * CH * 32; R.c4 = *(const f32x4*)(rc + X.tid * 4); R.s4 = *(const f32x4*)(rc + SEQ * 32 + X.tid * 4); }
; }
; template <int DK, bool RET>
; __device__ __forceinline__ void gla_local_item(const Ctx& X, bf16* H, int l, int r, LocRegs<RET>& R, bool has_next) {
;     static_assert(DK == 128 && !RET, "HGRN2 only (retention has its own path)");
;     const int b = r / 768, head = (r / 128) % 6, n = r % 128;
;     const float* LB = (const float*)(X.ws + WS_TAB);
;     unsigned char* St = (unsigned char*)(X.ws + WS_SHG); float* dd = (float*)(X.ws + WS_DHG);
;     const int kp = X.tid & 63;
.LBB0_298:
	s_add_i32 s25, s0, s62
	s_cmpk_gt_i32 s25, 0x5ff
	s_cselect_b64 s[12:13], -1, 0
	s_ashr_i32 s1, s0, 31
	s_lshr_b32 s1, s1, 25
	s_add_i32 s1, s0, s1
	s_ashr_i32 s14, s1, 7
	s_mul_hi_i32 s1, s14, 0x2aaaaaab
	s_lshr_b32 s15, s1, 31
	s_add_i32 s1, s1, s15
	s_mul_i32 s1, s1, 6
	s_sub_i32 s1, s14, s1
	s_lshl_b32 s16, s1, 7
	s_ashr_i32 s17, s16, 31
	s_lshl_b64 s[16:17], s[16:17], 2
	v_add_u32_e32 v28, 0, v93
	s_waitcnt vmcnt(4)
	ds_write_b16 v100, v22
	ds_write_b16_d16_hi v100, v22 offset:144
	ds_write_b16 v100, v23 offset:288
	ds_write_b16_d16_hi v100, v23 offset:432
	ds_write_b16 v100, v24 offset:576
	ds_write_b16_d16_hi v100, v24 offset:720
	ds_write_b16 v100, v25 offset:864
	ds_write_b16_d16_hi v100, v25 offset:1008
	ds_write_b16 v101, v18
	ds_write_b16_d16_hi v101, v18 offset:144
	ds_write_b16 v101, v19 offset:288
	ds_write_b16_d16_hi v101, v19 offset:432
	ds_write_b16 v101, v20 offset:576
	ds_write_b16_d16_hi v101, v20 offset:720
	ds_write_b16 v101, v21 offset:864
	ds_write_b16_d16_hi v101, v21 offset:1008
	ds_write_b128 v28, v[14:17] offset:40960
	ds_write_b128 v28, v[10:13] offset:49152
	ds_write_b128 v28, v[6:9] offset:57344
	v_add_u32_e32 v28, 0x10000, v28
	ds_write_b128 v28, v[2:5]
	v_mov_b32_e32 v60, v222
	v_mov_b32_e32 v61, v223
	v_mov_b32_e32 v26, v224
	v_mov_b32_e32 v27, v225
	s_and_b64 vcc, exec, s[12:13]
	s_cbranch_vccnz .LBB0_300
	s_mul_hi_i32 s15, s25, 0x2aaaaaab
	s_lshr_b32 s16, s15, 31
	s_lshr_b32 s15, s15, 7
	s_add_i32 s15, s15, s16
	s_ashr_i32 s16, s25, 31
	s_lshr_b32 s16, s16, 25
	s_add_i32 s16, s25, s16
	s_ashr_i32 s16, s16, 7
	s_mul_hi_i32 s17, s16, 0x2aaaaaab
	s_lshr_b32 s28, s17, 31
	s_add_i32 s17, s17, s28
	s_mul_i32 s17, s17, 6
	s_sub_i32 s28, s16, s17
	s_lshl_b32 s15, s15, 13
	s_lshl_b32 s16, s16, 13
	s_sub_i32 s15, s15, s16
	s_add_i32 s16, s23, s15
	s_lshl_b32 s15, s28, 7
	s_lshl_b32 s100, s15, 2
	s_mov_b32 s101, 0
	v_lshl_add_u64 v[222:223], v[48:49], 0, s[100:101]
	v_lshl_add_u64 v[224:225], v[46:47], 0, s[100:101]
	global_load_dwordx2 v[222:223], v[222:223], off
	global_load_dwordx2 v[224:225], v[224:225], off
	s_add_i32 s28, s15, 0x300
	v_add_u32_e32 v4, s28, v91
	s_ashr_i32 s17, s16, 31
	v_lshrrev_b32_e32 v158, 7, v4
	v_add_u32_e32 v8, s28, v92
	v_lshl_add_u64 v[2:3], s[16:17], 0, v[42:43]
	v_lshlrev_b64 v[4:5], 22, v[158:159]
	v_lshrrev_b32_e32 v158, 7, v8
	v_lshl_add_u64 v[4:5], s[4:5], 0, v[4:5]
	v_lshlrev_b64 v[2:3], 8, v[2:3]
	v_lshl_add_u64 v[6:7], s[16:17], 0, v[44:45]
	v_lshlrev_b64 v[8:9], 22, v[158:159]
	v_lshl_add_u64 v[4:5], v[4:5], 0, v[2:3]
	v_mov_b32_e32 v57, v159
	v_lshl_add_u64 v[8:9], s[4:5], 0, v[8:9]
	v_lshlrev_b64 v[6:7], 8, v[6:7]
	v_lshl_add_u64 v[4:5], v[4:5], 0, v[56:57]
	v_lshl_add_u64 v[8:9], v[8:9], 0, v[6:7]
	v_mov_b32_e32 v59, v159
	s_add_i32 s16, s15, 0x600
	v_lshl_add_u64 v[8:9], v[8:9], 0, v[58:59]
	global_load_dwordx4 v[22:25], v[4:5], off
	global_load_dwordx4 v[18:21], v[8:9], off
	v_add_u32_e32 v4, s16, v91
	v_lshrrev_b32_e32 v158, 7, v4
	v_add_u32_e32 v8, s16, v92
	v_lshlrev_b64 v[4:5], 22, v[158:159]
	v_lshrrev_b32_e32 v158, 7, v8
	v_lshl_add_u64 v[4:5], s[4:5], 0, v[4:5]
	v_lshlrev_b64 v[8:9], 22, v[158:159]
	v_lshl_add_u64 v[4:5], v[4:5], 0, v[2:3]
	v_lshl_add_u64 v[8:9], s[4:5], 0, v[8:9]
	v_lshl_add_u64 v[4:5], v[4:5], 0, v[56:57]
	v_lshl_add_u64 v[8:9], v[8:9], 0, v[6:7]
	s_addk_i32 s15, 0x900
	v_lshl_add_u64 v[8:9], v[8:9], 0, v[58:59]
	global_load_dwordx4 v[14:17], v[4:5], off
	global_load_dwordx4 v[10:13], v[8:9], off
	v_add_u32_e32 v4, s15, v91
	v_lshrrev_b32_e32 v158, 7, v4
	v_lshlrev_b64 v[4:5], 22, v[158:159]
	v_lshl_add_u64 v[4:5], s[4:5], 0, v[4:5]
	v_lshl_add_u64 v[2:3], v[4:5], 0, v[2:3]
	v_add_u32_e32 v4, s15, v92
	v_lshrrev_b32_e32 v158, 7, v4
	v_lshlrev_b64 v[4:5], 22, v[158:159]
	v_lshl_add_u64 v[4:5], s[4:5], 0, v[4:5]
	v_lshl_add_u64 v[4:5], v[4:5], 0, v[6:7]
	v_lshl_add_u64 v[2:3], v[2:3], 0, v[56:57]
	v_lshl_add_u64 v[4:5], v[4:5], 0, v[58:59]
	global_load_dwordx4 v[6:9], v[2:3], off
	s_nop 0
	global_load_dwordx4 v[2:5], v[4:5], off

; #define LAS __attribute__((address_space(3)))
; __device__ __forceinline__ f32x2v bfpair(unsigned w) { f32x2v r; r.x = __uint_as_float(w << 16); r.y = __uint_as_float(w & 0xffff0000u); return r; }
; __device__ __forceinline__ f32x2v rcp2(f32x2v v) { f32x2v r; r.x = __builtin_amdgcn_rcpf(v.x); r.y = __builtin_amdgcn_rcpf(v.y); return r; }
; template <int NC> __device__ __forceinline__ void raw_load(const Ctx& X, const bf16* H, size_t m0, int col, RawRegs<NC>& R) {
; #pragma unroll
;     for (int p = 0; p < NC / 64; ++p) { const int idx = X.tid + NTHR * p, r = idx / (NC / 8), c8 = idx % (NC / 8); R.w[p] = *(const v4u*)hptr(H, m0 + r, col + 8 * c8); }
; }
; template <int DIR, bool NEEDQ>
; __device__ __forceinline__ void gla_prep(lptr rawz, lptr rawq, f32x2v lb, LAS float* seg, int kp, int rg, f32x2v (&c)[8], f32x2v (&qv)[8], f32x2v (&kv)[8]) {
;     f32x2v run = (f32x2v){1.f, 1.f}; const f32x2v oml = 1.0f - lb;
; #pragma unroll
;     for (int i = 0; i < 8; ++i) { const int ii = DIR ? 7 - i : i; const int r = 8 * rg + ii;
;         const f32x2v z = bfpair(*(const LAS unsigned*)(rawz + (r * 128 + 2 * kp) * 2)); f32x2v e; e.x = __expf(-z.x); e.y = __expf(-z.y);
;         const f32x2v f = lb + oml * rcp2(e + 1.0f); run = run * f; kv[ii] = 1.0f - f; c[ii] = run;
;         if (NEEDQ) qv[ii] = bfpair(*(const LAS unsigned*)(rawq + (r * 128 + 2 * kp) * 2)); }
;     *(LAS f32x2v*)(seg + rg * 128 + 2 * kp) = run;
; }
.Lhg2_nopf:
	s_lshl_b32 s100, s84, 13
	s_lshl_b32 s101, s83, 13
	s_sub_i32 s100, s100, s101
	s_add_i32 s100, s80, s100
	s_ashr_i32 s101, s100, 31
	s_add_i32 s32, s14, 0x900
	v_add_u32_e32 v210, s32, v47
	v_lshrrev_b32_e32 v210, 7, v210
	v_mov_b32_e32 v211, 0
	v_lshlrev_b64 v[210:211], 22, v[210:211]
	v_lshl_add_u64 v[210:211], s[24:25], 0, v[210:211]
	v_lshl_add_u64 v[208:209], s[100:101], 0, v[44:45]
	v_lshlrev_b64 v[208:209], 8, v[208:209]
	v_lshl_add_u64 v[208:209], v[210:211], 0, v[208:209]
	v_mov_b32_e32 v210, v34
	v_mov_b32_e32 v211, 0
	v_lshl_add_u64 v[208:209], v[208:209], 0, v[210:211]
	global_load_dwordx4 v[200:203], v[208:209], off
	v_add_u32_e32 v210, s32, v112
	v_lshrrev_b32_e32 v210, 7, v210
	v_mov_b32_e32 v211, 0
	v_lshlrev_b64 v[210:211], 22, v[210:211]
	v_lshl_add_u64 v[210:211], s[24:25], 0, v[210:211]
	v_lshl_add_u64 v[208:209], s[100:101], 0, v[48:49]
	v_lshlrev_b64 v[208:209], 8, v[208:209]
	v_lshl_add_u64 v[208:209], v[210:211], 0, v[208:209]
	v_mov_b32_e32 v210, v60
	v_mov_b32_e32 v211, 0
	v_lshl_add_u64 v[208:209], v[208:209], 0, v[210:211]
	global_load_dwordx4 v[204:207], v[208:209], off
	s_add_u32 s98, s68, 0x200000
	s_addc_u32 s99, s69, 0
	v_lshl_add_u64 v[220:221], s[98:99], 0, v[54:55]
	global_load_dwordx4 v[212:215], v[220:221], off
	v_lshl_add_u64 v[220:221], s[98:99], 0, v[56:57]
	global_load_dwordx4 v[216:219], v[220:221], off
	v_readfirstlane_b32 s60, v35
	v_and_b32_e32 v90, 63, v35
	s_ashr_i32 s61, s60, 6
	v_lshlrev_b32_e32 v35, 2, v90
	v_lshl_or_b32 v91, s61, 11, v35
	s_add_i32 s63, 0, 0x14c00
	v_add_u32_e32 v36, s63, v91
	ds_read_b32 v36, v36
	s_add_i32 s82, 0, 0x18c00
	v_or_b32_e32 v40, 0x100, v91
	v_or_b32_e32 v68, 0x200, v91
	v_or_b32_e32 v74, 0x300, v91
	s_waitcnt lgkmcnt(0)
	v_lshlrev_b32_e32 v37, 16, v36
	v_and_b32_e32 v38, 0xffff0000, v36
	v_mul_f32_e32 v36, 0xbfb8aa3b, v37
	v_mul_f32_e32 v37, 0xbfb8aa3b, v38
	v_add_u32_e32 v38, s82, v91
	v_or_b32_e32 v78, 0x400, v91
	v_or_b32_e32 v80, 0x500, v91
	v_or_b32_e32 v96, 0x600, v91
	v_or_b32_e32 v91, 0x700, v91
	v_add_u32_e32 v98, s63, v91
	ds_read_b32 v61, v38
	ds_read_b32 v98, v98
	v_add_u32_e32 v38, s63, v40
	v_add_u32_e32 v40, s82, v40
	ds_read_b32 v38, v38
	ds_read_b32 v93, v40
	v_add_u32_e32 v40, s63, v68
	v_add_u32_e32 v68, s82, v68
	ds_read_b32 v40, v40
	ds_read_b32 v92, v68
	v_add_u32_e32 v68, s63, v74
	v_add_u32_e32 v74, s82, v74
	ds_read_b32 v68, v68
	ds_read_b32 v94, v74
	v_add_u32_e32 v74, s63, v78
	v_add_u32_e32 v78, s82, v78
	ds_read_b32 v74, v74
	ds_read_b32 v95, v78
	v_add_u32_e32 v78, s63, v80
	v_add_u32_e32 v80, s82, v80
	ds_read_b32 v78, v78
	ds_read_b32 v97, v80
	v_add_u32_e32 v80, s63, v96
	s_waitcnt lgkmcnt(9)
	v_lshlrev_b32_e32 v39, 16, v38
	v_and_b32_e32 v41, 0xffff0000, v38
	ds_read_b32 v80, v80
	v_mul_f32_e32 v38, 0xbfb8aa3b, v39
	v_mul_f32_e32 v39, 0xbfb8aa3b, v41
	s_waitcnt lgkmcnt(8)
	v_lshlrev_b32_e32 v41, 16, v40
	v_and_b32_e32 v64, 0xffff0000, v40
	v_exp_f32_e32 v36, v36
	v_exp_f32_e32 v37, v37
	v_exp_f32_e32 v38, v38
	v_exp_f32_e32 v39, v39
	v_mul_f32_e32 v40, 0xbfb8aa3b, v41
	v_mul_f32_e32 v41, 0xbfb8aa3b, v64
	s_waitcnt lgkmcnt(6)
	v_lshlrev_b32_e32 v69, 16, v68
	v_and_b32_e32 v72, 0xffff0000, v68
	v_exp_f32_e32 v40, v40
	v_exp_f32_e32 v41, v41
	v_mul_f32_e32 v68, 0xbfb8aa3b, v69
	v_mul_f32_e32 v69, 0xbfb8aa3b, v72
	s_waitcnt lgkmcnt(4)
	v_lshlrev_b32_e32 v75, 16, v74
	v_and_b32_e32 v76, 0xffff0000, v74
	v_exp_f32_e32 v68, v68
	v_exp_f32_e32 v69, v69
	v_mul_f32_e32 v74, 0xbfb8aa3b, v75
	v_mul_f32_e32 v75, 0xbfb8aa3b, v76
	s_waitcnt lgkmcnt(2)
	v_lshlrev_b32_e32 v79, 16, v78
	v_and_b32_e32 v81, 0xffff0000, v78
	v_add_u32_e32 v96, s82, v96
	v_exp_f32_e32 v74, v74
	v_exp_f32_e32 v75, v75
	v_mul_f32_e32 v78, 0xbfb8aa3b, v79
	v_mul_f32_e32 v79, 0xbfb8aa3b, v81
	ds_read_b32 v96, v96
	s_waitcnt lgkmcnt(1)
	v_lshlrev_b32_e32 v81, 16, v80
	v_and_b32_e32 v82, 0xffff0000, v80
	v_pk_add_f32 v[36:37], v[36:37], 1.0 op_sel_hi:[1,0]
	v_pk_add_f32 v[38:39], v[38:39], 1.0 op_sel_hi:[1,0]
	v_exp_f32_e32 v78, v78
	v_exp_f32_e32 v79, v79
	v_mul_f32_e32 v80, 0xbfb8aa3b, v81
	v_mul_f32_e32 v81, 0xbfb8aa3b, v82
	v_lshlrev_b32_e32 v99, 16, v98
	v_and_b32_e32 v100, 0xffff0000, v98
	v_rcp_f32_e32 v36, v36
	v_rcp_f32_e32 v37, v37
	v_rcp_f32_e32 v38, v38
	v_rcp_f32_e32 v39, v39
	v_pk_add_f32 v[40:41], v[40:41], 1.0 op_sel_hi:[1,0]
	v_exp_f32_e32 v80, v80
	v_exp_f32_e32 v81, v81
	v_mul_f32_e32 v98, 0xbfb8aa3b, v99
	v_mul_f32_e32 v99, 0xbfb8aa3b, v100
	v_rcp_f32_e32 v40, v40
	v_rcp_f32_e32 v41, v41
	v_pk_add_f32 v[68:69], v[68:69], 1.0 op_sel_hi:[1,0]
	v_exp_f32_e32 v98, v98
	v_exp_f32_e32 v99, v99
	v_rcp_f32_e32 v68, v68
	v_rcp_f32_e32 v69, v69
	v_pk_add_f32 v[74:75], v[74:75], 1.0 op_sel_hi:[1,0]
	v_pk_add_f32 v[88:89], v[86:87], 1.0 op_sel_hi:[1,0] neg_lo:[1,0] neg_hi:[1,0]
	v_rcp_f32_e32 v74, v74
	v_rcp_f32_e32 v75, v75
	v_pk_add_f32 v[78:79], v[78:79], 1.0 op_sel_hi:[1,0]
	v_pk_fma_f32 v[36:37], v[88:89], v[36:37], v[86:87]
	v_pk_fma_f32 v[70:71], v[88:89], v[38:39], v[86:87]
	v_rcp_f32_e32 v78, v78
	v_rcp_f32_e32 v79, v79
	v_pk_add_f32 v[80:81], v[80:81], 1.0 op_sel_hi:[1,0]
	v_pk_mul_f32 v[38:39], v[36:37], v[70:71]
	v_pk_fma_f32 v[64:65], v[88:89], v[40:41], v[86:87]
	v_rcp_f32_e32 v80, v80
	v_rcp_f32_e32 v81, v81
	v_pk_add_f32 v[98:99], v[98:99], 1.0 op_sel_hi:[1,0]
	v_pk_mul_f32 v[40:41], v[38:39], v[64:65]
	v_pk_fma_f32 v[72:73], v[88:89], v[68:69], v[86:87]
	v_rcp_f32_e32 v98, v98
	v_rcp_f32_e32 v99, v99
	v_pk_mul_f32 v[68:69], v[40:41], v[72:73]
	v_pk_fma_f32 v[76:77], v[88:89], v[74:75], v[86:87]
	v_pk_fma_f32 v[84:85], v[88:89], v[78:79], v[86:87]
	v_pk_mul_f32 v[74:75], v[68:69], v[76:77]
	v_pk_fma_f32 v[82:83], v[88:89], v[80:81], v[86:87]
	v_pk_mul_f32 v[78:79], v[74:75], v[84:85]
	s_lshl_b32 s68, s61, 9
	v_pk_mul_f32 v[80:81], v[78:79], v[82:83]
	v_pk_fma_f32 v[88:89], v[88:89], v[98:99], v[86:87]
	s_add_i32 s68, s74, s68
	v_lshlrev_b32_e32 v99, 3, v90
	v_pk_mul_f32 v[86:87], v[80:81], v[88:89]
	v_add_u32_e32 v91, s82, v91
	v_add_u32_e32 v90, s68, v99
	ds_read_b32 v98, v91
	ds_write_b64 v90, v[86:87]
	v_cvt_pk_f32_fp8_e32 v[90:91], v30
	s_waitcnt lgkmcnt(0)
	s_barrier
; #define LAS __attribute__((address_space(3)))
; __device__ __forceinline__ unsigned pk2(float lo, float hi) { return pg8::cvt_pk_bf16(lo, hi); }
; __device__ __forceinline__ f32x2v f8lo(unsigned w) { return __builtin_amdgcn_cvt_pk_f32_fp8((int)w, false); }
; __device__ __forceinline__ f32x2v f8hi(unsigned w) { return __builtin_amdgcn_cvt_pk_f32_fp8((int)w, true); }
; template <int DK, bool RET, int DIR>
; __device__ __forceinline__ void gla_out_dir(const Ctx& X, int chain, int n, f32x2v lb, const unsigned char* St, f32x4 (&o)[4], const bf16* H, size_t m0, int zbcol) {
;     ...
;         for (int p = 0; p < 2; ++p) { const int idx = X.tid + NTHR * p; const lptr d = ST + (idx >> 3) * 272 + (idx & 7) * 32;
;             v4u a, b; f32x2v f;
;             f = f8lo(sr[p].x); a.x = pk2(f.x, f.y); f = f8hi(sr[p].x); a.y = pk2(f.x, f.y); f = f8lo(sr[p].y); a.z = pk2(f.x, f.y); f = f8hi(sr[p].y); a.w = pk2(f.x, f.y);
;             f = f8lo(sr[p].z); b.x = pk2(f.x, f.y); f = f8hi(sr[p].z); b.y = pk2(f.x, f.y); f = f8lo(sr[p].w); b.z = pk2(f.x, f.y); f = f8hi(sr[p].w); b.w = pk2(f.x, f.y);
;             *(LAS v4u*)d = a; *(LAS v4u*)(d + 16) = b; }
;         {
;             const int sg = DIR ? 7 - rg : rg, ss = sg >> 2, hq = sg & 3;
;             const f32x2v T0 = SEGT(0), T1 = SEGT(1), T2 = SEGT(2), T3 = SEGT(3), sub0 = (T0 * T1) * (T2 * T3);
;             f32x2v pq = (f32x2v){1.f, 1.f};
; #pragma unroll
;             for (int j = 0; j < 3; ++j) if (j < hq) pq = pq * SEGT(4 * ss + j);
	v_cvt_pk_bf16_f32 v100, v90, v91
	v_cvt_pk_f32_fp8_sdwa v[90:91], v30 src0_sel:WORD_1
	s_and_b32 s68, s61, 3
	s_and_b32 s69, s61, -4
	s_cmp_eq_u32 s68, 0
	v_cvt_pk_bf16_f32 v101, v90, v91
	v_cvt_pk_f32_fp8_e32 v[90:91], v31
	v_cvt_pk_f32_fp8_sdwa v[30:31], v31 src0_sel:WORD_1
	v_cvt_pk_bf16_f32 v102, v90, v91
	v_cvt_pk_bf16_f32 v103, v30, v31
	v_cvt_pk_f32_fp8_e32 v[30:31], v32
	v_cvt_pk_f32_fp8_sdwa v[90:91], v32 src0_sel:WORD_1
	v_cvt_pk_bf16_f32 v30, v30, v31
	v_cvt_pk_bf16_f32 v31, v90, v91
	v_cvt_pk_f32_fp8_e32 v[90:91], v33
	v_cvt_pk_bf16_f32 v32, v90, v91
	v_cvt_pk_f32_fp8_sdwa v[90:91], v33 src0_sel:WORD_1
	v_cvt_pk_bf16_f32 v33, v90, v91
	ds_write_b128 v140, v[100:103]
	ds_write_b128 v140, v[30:33] offset:16
	v_cvt_pk_f32_fp8_e32 v[30:31], v26
	v_cvt_pk_f32_fp8_sdwa v[32:33], v26 src0_sel:WORD_1
	v_cvt_pk_f32_fp8_sdwa v[90:91], v28 src0_sel:WORD_1
	v_cvt_pk_bf16_f32 v30, v30, v31
	v_cvt_pk_bf16_f32 v31, v32, v33
	v_cvt_pk_f32_fp8_e32 v[32:33], v27
	v_cvt_pk_f32_fp8_sdwa v[26:27], v27 src0_sel:WORD_1
	v_cvt_pk_bf16_f32 v32, v32, v33
	v_cvt_pk_bf16_f32 v33, v26, v27
	v_cvt_pk_f32_fp8_e32 v[26:27], v28
	v_cvt_pk_bf16_f32 v26, v26, v27
	v_cvt_pk_bf16_f32 v27, v90, v91
	v_cvt_pk_f32_fp8_e32 v[90:91], v29
	v_cvt_pk_bf16_f32 v28, v90, v91
	v_cvt_pk_f32_fp8_sdwa v[90:91], v29 src0_sel:WORD_1
	v_cvt_pk_bf16_f32 v29, v90, v91
	ds_write_b128 v141, v[30:33]
	ds_write_b128 v141, v[26:29] offset:16
	v_add_u32_e32 v29, 0, v99
	v_add_u32_e32 v28, s74, v99
	v_add_u32_e32 v30, 0x13a00, v29
	v_add_u32_e32 v32, 0x13c00, v29
	v_add_u32_e32 v29, 0x13e00, v29
	ds_read_b64 v[26:27], v28
	ds_read_b64 v[30:31], v30
	ds_read_b64 v[32:33], v32
	ds_read_b64 v[90:91], v29
	v_lshl_add_u32 v99, s69, 9, v28
	s_cbranch_scc1 .LBB0_564
	ds_read_b64 v[28:29], v99
	s_cmp_lt_u32 s68, 2
	s_cbranch_scc1 .LBB0_483

; #define LAS __attribute__((address_space(3)))
; __device__ __forceinline__ unsigned pk2(float lo, float hi) { return pg8::cvt_pk_bf16(lo, hi); }
; #define MFMA16(a, b, c) __builtin_amdgcn_mfma_f32_16x16x32_bf16((a), (b), (c), 0, 0, 0)
; template <int DK, bool RET, int DIR>
; __device__ __forceinline__ void gla_out_dir(const Ctx& X, int chain, int n, f32x2v lb, const unsigned char* St, f32x4 (&o)[4], const bf16* H, size_t m0, int zbcol) {
;     ...
;     RawRegs<128> zbr; if (!RET && DIR == 0) raw_load<128>(X, H, m0, zbcol, zbr);
; #pragma unroll
;     for (int bi = 0; bi < 2; ++bi) { const int blk = 2 * X.wave + bi, I = blk >> 2, J = blk & 3; const int sI = DIR ? 3 - I : I, sJ = DIR ? 3 - J : J;
;         v2u w; w.x = 0u; w.y = 0u;
;         if (sJ <= sI) { const bool same = (sI >> 1) == (sJ >> 1); const lptr KS = same ? KD : KH; const int krow = same ? 16 * J + fr : (DIR ? 16 * J + fr - 32 : 16 * J + fr);
;             f32x4 acc = (f32x4){0.f, 0.f, 0.f, 0.f};
; #pragma unroll
;             for (int ks = 0; ks < DK / 32; ++ks) { const bf16x8 a = ldsfrag(KS, krow, SQ, 32 * ks + 8 * fq); const bf16x8 bb = ldsfrag(Q0, 16 * I + fr, SQ, 32 * ks + 8 * fq); acc = MFMA16(a, bb, acc); }
;             if (sI == sJ) {
; #pragma unroll
;                 for (int j = 0; j < 4; ++j) { const int jl = 4 * fq + j; const bool keep = DIR ? (jl >= fr) : (jl <= fr); if (!keep) acc[j] = 0.f; } }
;             w.x = pk2(acc[0], acc[1]); w.y = pk2(acc[2], acc[3]); }
;         *(LAS v2u*)(AM + (16 * I + fr) * 144 + (16 * J + 4 * fq) * 2) = w; }
.LBB0_517:
	s_lshl_b32 s60, s84, 13
	s_lshl_b32 s61, s83, 13
	s_sub_i32 s60, s60, s61
	s_add_i32 s68, s80, s60
	s_ashr_i32 s69, s68, 31
	s_add_i32 s60, s14, 0x900
	v_add_u32_e32 v28, s60, v47
	v_lshrrev_b32_e32 v158, 7, v28
	v_lshl_add_u64 v[26:27], s[68:69], 0, v[44:45]
	v_lshlrev_b64 v[28:29], 22, v[158:159]
	v_add_u32_e32 v30, s60, v112
	v_lshl_add_u64 v[28:29], s[24:25], 0, v[28:29]
	v_lshlrev_b64 v[26:27], 8, v[26:27]
	v_lshrrev_b32_e32 v158, 7, v30
	v_lshl_add_u64 v[26:27], v[28:29], 0, v[26:27]
	v_lshl_add_u64 v[28:29], s[68:69], 0, v[48:49]
	v_lshlrev_b64 v[30:31], 22, v[158:159]
	v_lshl_add_u64 v[30:31], s[24:25], 0, v[30:31]
	v_lshlrev_b64 v[28:29], 8, v[28:29]
	v_mov_b32_e32 v35, v159
	v_lshl_add_u64 v[28:29], v[30:31], 0, v[28:29]
	v_mov_b32_e32 v61, v159
	s_waitcnt lgkmcnt(0)
	s_barrier
	v_lshl_add_u64 v[26:27], v[26:27], 0, v[34:35]
	v_lshl_add_u64 v[30:31], v[28:29], 0, v[60:61]
	v_mov_b32_e32 v34, 0
	s_andn2_b64 vcc, exec, s[36:37]
	v_mov_b32_e32 v36, 0
	v_mov_b32_e32 v37, 0
	s_cbranch_vccnz .LBB0_519
	ds_read_b128 v[36:39], v130
	ds_read_b128 v[68:71], v142
	s_and_b64 s[60:61], s[16:17], s[46:47]
	s_waitcnt lgkmcnt(0)
	v_mfma_f32_16x16x32_bf16 v[36:39], v[36:39], v[68:71], 0
	ds_read_b128 v[68:71], v130 offset:64
	ds_read_b128 v[72:75], v142 offset:64
	s_waitcnt lgkmcnt(0)
	v_mfma_f32_16x16x32_bf16 v[36:39], v[68:71], v[72:75], v[36:39]
	ds_read_b128 v[68:71], v130 offset:128
	ds_read_b128 v[72:75], v142 offset:128
	s_waitcnt lgkmcnt(0)
	v_mfma_f32_16x16x32_bf16 v[36:39], v[68:71], v[72:75], v[36:39]
	ds_read_b128 v[68:71], v130 offset:192
	ds_read_b128 v[72:75], v142 offset:192
	s_waitcnt lgkmcnt(0)
	v_mfma_f32_16x16x32_bf16 v[36:39], v[68:71], v[72:75], v[36:39]
	s_nop 7
	v_cndmask_b32_e64 v38, v38, 0, s[60:61]
	s_and_b64 s[60:61], s[60:61], s[44:45]
	v_cndmask_b32_e64 v37, v37, 0, s[60:61]
	s_and_b64 s[60:61], s[60:61], s[42:43]
	v_cndmask_b32_e64 v35, v39, 0, s[16:17]
	v_cndmask_b32_e64 v36, v36, 0, s[60:61]
	v_cvt_pk_bf16_f32 v36, v36, v37
	v_cvt_pk_bf16_f32 v37, v38, v35

; #define MFMA16(a, b, c) __builtin_amdgcn_mfma_f32_16x16x32_bf16((a), (b), (c), 0, 0, 0)
; template <int DK, bool RET, int DIR>
; __device__ __forceinline__ void gla_out_dir(const Ctx& X, int chain, int n, f32x2v lb, const unsigned char* St, f32x4 (&o)[4], const bf16* H, size_t m0, int zbcol) {
;     ...
;     {
;         const int stb = DIR ? 3 - tb : tb; const int r = 16 * tb + fr;
; #pragma unroll
;         for (int ks = 0; ks < 2; ++ks) { const bf16x8 bb = ldsfrag(AM, r, 144, 32 * ks + 8 * fq);
; #pragma unroll
;             for (int vt = 0; vt < 4; ++vt) { const bf16x8 a = vtfrag(VT, 64 * vh + 16 * vt + fr, 144, 32 * ks + 8 * fq); o[vt] = MFMA16(a, bb, o[vt]); } }
;         const lptr QI = (stb >> 1) ? Q1 : Q0; const int qrow = (stb >> 1) ? (DIR ? r : r - 32) : r;
; #pragma unroll
;         for (int ks = 0; ks < DK / 32; ++ks) { const bf16x8 bb = ldsfrag(QI, qrow, SQ, 32 * ks + 8 * fq);
; #pragma unroll
;             for (int vt = 0; vt < 4; ++vt) { const bf16x8 a = ldsfrag(ST, 64 * vh + 16 * vt + fr, 272, 32 * ks + 8 * fq); o[vt] = MFMA16(a, bb, o[vt]); } }
;     }
;     if (!RET && DIR == 0) raw_store<128>(X, X.lds + L::RAW, zbr);
; template <int DK, bool RET>
; __device__ __forceinline__ void gla_out_item(const Ctx& X, const bf16* H, bf16* Y, int l, int r, OutRegs<RET>& R, bool has_next) {
;     ...
;     for (int t = 0; t < 4; ++t) gw[t] = *(const v2u*)hptr(H, m, C_HGG + head * 128 + 64 * vh + 16 * t + 4 * fq);
;     gla_out_dir<DK, RET, 1>(X, chain + 1, n, lb1, St, o, H, m0, 0);
.LBB0_521:
	ds_write_b64 v144, v[34:35]
	s_waitcnt lgkmcnt(0)
	s_barrier
	v_add_u32_e32 v173, v118, v43
	ds_read_b128 v[34:37], v145 offset:52224
	ds_read_b128 v[38:41], v173
	ds_read_b128 v[68:71], v146 offset:52224
	ds_read_b128 v[72:75], v147 offset:52224
	ds_read_b128 v[76:79], v148 offset:52224
	s_waitcnt lgkmcnt(2)
	v_mfma_f32_16x16x32_bf16 v[68:71], v[68:71], v[38:41], 0
	ds_read_b128 v[80:83], v150 offset:52224
	ds_read_b128 v[84:87], v149
	v_add_u32_e32 v172, v124, v115
	v_add_u32_e32 v171, v125, v115
	v_mfma_f32_16x16x32_bf16 v[34:37], v[34:37], v[38:41], 0
	v_add_u32_e32 v170, v126, v115
	v_add_u32_e32 v169, v127, v115
	v_add_u32_e32 v168, v124, v116
	s_waitcnt lgkmcnt(3)
	v_mfma_f32_16x16x32_bf16 v[72:75], v[72:75], v[38:41], 0
	v_add_u32_e32 v166, v126, v116
	v_add_u32_e32 v158, v125, v116
	v_add_u32_e32 v167, v127, v116
	s_waitcnt lgkmcnt(2)
	v_mfma_f32_16x16x32_bf16 v[38:41], v[76:79], v[38:41], 0
	ds_read_b128 v[76:79], v151 offset:52224
	v_add_u32_e32 v157, v124, v117
	v_add_u32_e32 v156, v126, v117
	s_waitcnt lgkmcnt(1)
	v_mfma_f32_16x16x32_bf16 v[34:37], v[80:83], v[84:87], v[34:37]
	ds_read_b128 v[80:83], v152 offset:52224
	v_add_u32_e32 v64, s68, v113
	v_add_u32_e32 v155, v125, v117
	s_waitcnt lgkmcnt(1)
	v_mfma_f32_16x16x32_bf16 v[68:71], v[76:79], v[84:87], v[68:71]
	ds_read_b128 v[76:79], v153 offset:52224
	v_add_u32_e32 v61, v127, v117
	v_ashrrev_i32_e32 v65, 31, v64
	s_waitcnt lgkmcnt(1)
	v_mfma_f32_16x16x32_bf16 v[72:75], v[80:83], v[84:87], v[72:75]
	ds_read_b128 v[80:83], v154
	ds_read_b128 v[88:91], v132
	ds_read_b128 v[92:95], v154 offset:4352
	s_or_b32 s60, s62, 1
	v_lshlrev_b64 v[64:65], 8, v[64:65]
	s_waitcnt lgkmcnt(3)
	v_mfma_f32_16x16x32_bf16 v[38:41], v[76:79], v[84:87], v[38:41]
	ds_read_b128 v[76:79], v132 offset:64
	s_ashr_i32 s61, s60, 31
	v_lshl_add_u64 v[64:65], s[24:25], 0, v[64:65]
	s_waitcnt lgkmcnt(2)
	v_mfma_f32_16x16x32_bf16 v[34:37], v[80:83], v[88:91], v[34:37]
	ds_read_b128 v[80:83], v154 offset:8704
	ds_read_b128 v[84:87], v154 offset:13056
	s_lshl_b64 s[60:61], s[60:61], 21
	s_add_u32 s60, s77, s60
	s_waitcnt lgkmcnt(3)
	v_mfma_f32_16x16x32_bf16 v[68:71], v[92:95], v[88:91], v[68:71]
	ds_read_b128 v[92:95], v172
	ds_read_b128 v[96:99], v171
	s_addc_u32 s61, s78, s61
	s_add_u32 s0, s60, s0
	s_waitcnt lgkmcnt(3)
	v_mfma_f32_16x16x32_bf16 v[72:75], v[80:83], v[88:91], v[72:75]
	ds_read_b128 v[80:83], v170
	ds_read_b128 v[100:103], v169
	s_addc_u32 s1, s61, s1
	s_mov_b64 s[64:65], s[20:21]
	s_waitcnt lgkmcnt(4)
	v_mfma_f32_16x16x32_bf16 v[38:41], v[84:87], v[88:91], v[38:41]
	ds_read_b128 v[84:87], v168
	ds_read_b128 v[88:91], v158
	s_waitcnt lgkmcnt(5)
	v_mfma_f32_16x16x32_bf16 v[34:37], v[92:95], v[76:79], v[34:37]
	ds_read_b128 v[92:95], v166
	ds_read_b128 v[104:107], v167
	s_waitcnt lgkmcnt(6)
	v_mfma_f32_16x16x32_bf16 v[68:71], v[96:99], v[76:79], v[68:71]
	ds_read_b128 v[96:99], v132 offset:128
	ds_read_b128 v[108:111], v132 offset:192
	s_waitcnt lgkmcnt(6)
	v_mfma_f32_16x16x32_bf16 v[38:41], v[100:103], v[76:79], v[38:41]
	s_waitcnt lgkmcnt(1)
	v_mfma_f32_16x16x32_bf16 v[34:37], v[84:87], v[96:99], v[34:37]
	v_add_u32_e32 v84, s63, v114
	v_mfma_f32_16x16x32_bf16 v[72:75], v[80:83], v[76:79], v[72:75]
	ds_read_b128 v[80:83], v157
	ds_read_b128 v[174:177], v155
	ds_read_b128 v[76:79], v156
	ds_read_b128 v[100:103], v61
	s_waitcnt vmcnt(0)
	ds_write_b128 v84, v[200:203]
	ds_write_b128 v63, v[204:207]
	v_add_u32_e32 v63, s14, v119
	v_mfma_f32_16x16x32_bf16 v[84:87], v[104:107], v[96:99], v[38:41]
	s_waitcnt lgkmcnt(0)
	s_barrier
	v_mfma_f32_16x16x32_bf16 v[26:29], v[88:91], v[96:99], v[68:71]
	s_nop 0
	v_ashrrev_i32_e32 v38, 7, v63
	v_ashrrev_i32_e32 v39, 31, v38
	v_lshlrev_b64 v[68:69], 22, v[38:39]
	s_waitcnt lgkmcnt(5)
	v_mfma_f32_16x16x32_bf16 v[38:41], v[80:83], v[108:111], v[34:37]
	v_mov_b32_e32 v63, v159
	s_nop 1
	v_lshl_add_u64 v[34:35], v[64:65], 0, v[68:69]
	v_mfma_f32_16x16x32_bf16 v[30:33], v[92:95], v[96:99], v[72:75]
	v_lshl_add_u64 v[64:65], v[34:35], 0, v[62:63]
	v_mov_b32_e32 v63, v42
	s_nop 0
	global_load_dwordx2 v[72:73], v[64:65], off
	global_load_dwordx2 v[70:71], v[64:65], off offset:32
	global_load_dwordx2 v[68:69], v[64:65], off offset:64
	s_nop 0
	global_load_dwordx2 v[64:65], v[64:65], off offset:96
	s_waitcnt lgkmcnt(3)
	v_mfma_f32_16x16x32_bf16 v[30:33], v[76:79], v[108:111], v[30:33]
	v_readfirstlane_b32 s62, v63
	v_and_b32_e32 v161, 63, v63
	s_ashr_i32 s70, s62, 6
	v_lshlrev_b32_e32 v63, 2, v161
	v_lshl_or_b32 v88, s70, 11, v63
	v_or_b32_e32 v78, 0x700, v88
	v_or_b32_e32 v80, 0x600, v88
	v_or_b32_e32 v82, 0x500, v88
	v_mfma_f32_16x16x32_bf16 v[34:37], v[174:177], v[108:111], v[26:29]
	v_lshl_add_u64 v[74:75], s[0:1], 0, v[54:55]
	v_add_u32_e32 v79, s63, v78
	v_add_u32_e32 v81, s63, v80
	s_waitcnt lgkmcnt(2)
	v_mfma_f32_16x16x32_bf16 v[26:29], v[100:103], v[108:111], v[84:87]
	v_add_u32_e32 v83, s63, v82
	v_add_u32_e32 v82, s82, v82
	v_lshl_add_u64 v[76:77], s[0:1], 0, v[56:57]
	v_or_b32_e32 v84, 0x400, v88
	v_add_u32_e32 v78, s82, v78
	v_add_u32_e32 v80, s82, v80
	v_add_u32_e32 v85, s63, v84
	v_add_u32_e32 v84, s82, v84
	ds_read_b32 v79, v79
	ds_read_b32 v174, v78
	ds_read_b32 v81, v81
	ds_read_b32 v175, v80
	ds_read_b32 v83, v83
	ds_read_b32 v176, v82
	ds_read_b32 v82, v85
	ds_read_b32 v177, v84
	v_mov_b32_e32 v104, v212
	v_mov_b32_e32 v105, v213
	v_mov_b32_e32 v106, v214
	v_mov_b32_e32 v107, v215
	v_mov_b32_e32 v108, v216
	v_mov_b32_e32 v109, v217
	v_mov_b32_e32 v110, v218
	v_mov_b32_e32 v111, v219
	s_waitcnt lgkmcnt(7)
	v_lshlrev_b32_e32 v78, 16, v79
	v_and_b32_e32 v79, 0xffff0000, v79
	v_mul_f32_e32 v78, 0xbfb8aa3b, v78
	v_mul_f32_e32 v79, 0xbfb8aa3b, v79
	s_waitcnt lgkmcnt(5)
; #define LAS __attribute__((address_space(3)))
; __device__ __forceinline__ unsigned pk2(float lo, float hi) { return pg8::cvt_pk_bf16(lo, hi); }
; __device__ __forceinline__ f32x2v f8lo(unsigned w) { return __builtin_amdgcn_cvt_pk_f32_fp8((int)w, false); }
; __device__ __forceinline__ f32x2v f8hi(unsigned w) { return __builtin_amdgcn_cvt_pk_f32_fp8((int)w, true); }
; __device__ __forceinline__ f32x2v bfpair(unsigned w) { f32x2v r; r.x = __uint_as_float(w << 16); r.y = __uint_as_float(w & 0xffff0000u); return r; }
; __device__ __forceinline__ f32x2v rcp2(f32x2v v) { f32x2v r; r.x = __builtin_amdgcn_rcpf(v.x); r.y = __builtin_amdgcn_rcpf(v.y); return r; }
; template <int DIR, bool NEEDQ>
; __device__ __forceinline__ void gla_prep(lptr rawz, lptr rawq, f32x2v lb, LAS float* seg, int kp, int rg, f32x2v (&c)[8], f32x2v (&qv)[8], f32x2v (&kv)[8]) {
;     f32x2v run = (f32x2v){1.f, 1.f}; const f32x2v oml = 1.0f - lb;
; #pragma unroll
;     for (int i = 0; i < 8; ++i) { const int ii = DIR ? 7 - i : i; const int r = 8 * rg + ii;
;         const f32x2v z = bfpair(*(const LAS unsigned*)(rawz + (r * 128 + 2 * kp) * 2)); f32x2v e; e.x = __expf(-z.x); e.y = __expf(-z.y);
;         const f32x2v f = lb + oml * rcp2(e + 1.0f); run = run * f; kv[ii] = 1.0f - f; c[ii] = run;
;         if (NEEDQ) qv[ii] = bfpair(*(const LAS unsigned*)(rawq + (r * 128 + 2 * kp) * 2)); }
;     *(LAS f32x2v*)(seg + rg * 128 + 2 * kp) = run;
; }
; template <int DK, bool RET, int DIR>
; __device__ __forceinline__ void gla_out_dir(const Ctx& X, int chain, int n, f32x2v lb, const unsigned char* St, f32x4 (&o)[4], const bf16* H, size_t m0, int zbcol) {
;     ...
;         for (int p = 0; p < 2; ++p) { const int idx = X.tid + NTHR * p; const lptr d = ST + (idx >> 3) * 272 + (idx & 7) * 32;
;             v4u a, b; f32x2v f;
;             f = f8lo(sr[p].x); a.x = pk2(f.x, f.y); f = f8hi(sr[p].x); a.y = pk2(f.x, f.y); f = f8lo(sr[p].y); a.z = pk2(f.x, f.y); f = f8hi(sr[p].y); a.w = pk2(f.x, f.y);
;             f = f8lo(sr[p].z); b.x = pk2(f.x, f.y); f = f8hi(sr[p].z); b.y = pk2(f.x, f.y); f = f8lo(sr[p].w); b.z = pk2(f.x, f.y); f = f8hi(sr[p].w); b.w = pk2(f.x, f.y);
;             *(LAS v4u*)d = a; *(LAS v4u*)(d + 16) = b; }
	v_lshlrev_b32_e32 v80, 16, v81
	v_and_b32_e32 v81, 0xffff0000, v81
	v_exp_f32_e32 v78, v78
	v_exp_f32_e32 v79, v79
	v_mul_f32_e32 v80, 0xbfb8aa3b, v80
	v_mul_f32_e32 v81, 0xbfb8aa3b, v81
	v_exp_f32_e32 v80, v80
	v_exp_f32_e32 v81, v81
	v_pk_add_f32 v[78:79], v[78:79], 1.0 op_sel_hi:[1,0]
	v_pk_add_f32 v[86:87], v[66:67], 1.0 op_sel_hi:[1,0] neg_lo:[1,0] neg_hi:[1,0]
	v_rcp_f32_e32 v78, v78
	v_rcp_f32_e32 v79, v79
	v_pk_add_f32 v[80:81], v[80:81], 1.0 op_sel_hi:[1,0]
	v_or_b32_e32 v89, 0x300, v88
	v_rcp_f32_e32 v80, v80
	v_rcp_f32_e32 v81, v81
	v_or_b32_e32 v91, 0x200, v88
	v_pk_fma_f32 v[74:75], v[86:87], v[78:79], v[66:67]
	s_waitcnt lgkmcnt(3)
	v_lshlrev_b32_e32 v78, 16, v83
	v_and_b32_e32 v79, 0xffff0000, v83
	v_add_u32_e32 v90, s63, v89
	v_add_u32_e32 v92, s63, v91
	v_or_b32_e32 v93, 0x100, v88
	v_pk_fma_f32 v[76:77], v[86:87], v[80:81], v[66:67]
	v_mul_f32_e32 v78, 0xbfb8aa3b, v78
	v_mul_f32_e32 v79, 0xbfb8aa3b, v79
	s_waitcnt lgkmcnt(1)
	v_lshlrev_b32_e32 v80, 16, v82
	v_and_b32_e32 v81, 0xffff0000, v82
	v_add_u32_e32 v89, s82, v89
	v_add_u32_e32 v91, s82, v91
	v_add_u32_e32 v94, s63, v93
	v_add_u32_e32 v93, s82, v93
	v_add_u32_e32 v95, s63, v88
	v_add_u32_e32 v88, s82, v88
	ds_read_b32 v90, v90
	ds_read_b32 v178, v89
	ds_read_b32 v92, v92
	ds_read_b32 v179, v91
	ds_read_b32 v96, v94
	ds_read_b32 v180, v93
	ds_read_b32 v98, v95
	ds_read_b32 v181, v88
	v_exp_f32_e32 v78, v78
	v_exp_f32_e32 v79, v79
	v_mul_f32_e32 v80, 0xbfb8aa3b, v80
	v_mul_f32_e32 v81, 0xbfb8aa3b, v81
	s_waitcnt lgkmcnt(7)
	v_lshlrev_b32_e32 v88, 16, v90
	v_and_b32_e32 v89, 0xffff0000, v90
	v_exp_f32_e32 v80, v80
	v_exp_f32_e32 v81, v81
	v_mul_f32_e32 v88, 0xbfb8aa3b, v88
	v_mul_f32_e32 v89, 0xbfb8aa3b, v89
	s_waitcnt lgkmcnt(5)
	v_lshlrev_b32_e32 v90, 16, v92
	v_and_b32_e32 v91, 0xffff0000, v92
	v_exp_f32_e32 v88, v88
	v_exp_f32_e32 v89, v89
	v_mul_f32_e32 v90, 0xbfb8aa3b, v90
	v_mul_f32_e32 v91, 0xbfb8aa3b, v91
	s_waitcnt lgkmcnt(3)
	v_lshlrev_b32_e32 v97, 16, v96
	v_and_b32_e32 v99, 0xffff0000, v96
	v_exp_f32_e32 v90, v90
	v_exp_f32_e32 v91, v91
	v_mul_f32_e32 v96, 0xbfb8aa3b, v97
	v_mul_f32_e32 v97, 0xbfb8aa3b, v99
	s_waitcnt lgkmcnt(1)
	v_lshlrev_b32_e32 v99, 16, v98
	v_and_b32_e32 v100, 0xffff0000, v98
	v_pk_add_f32 v[78:79], v[78:79], 1.0 op_sel_hi:[1,0]
	v_exp_f32_e32 v96, v96
	v_exp_f32_e32 v97, v97
	v_mul_f32_e32 v98, 0xbfb8aa3b, v99
	v_mul_f32_e32 v99, 0xbfb8aa3b, v100
	v_rcp_f32_e32 v82, v78
	v_rcp_f32_e32 v83, v79
	v_pk_add_f32 v[78:79], v[80:81], 1.0 op_sel_hi:[1,0]
	v_exp_f32_e32 v98, v98
	v_exp_f32_e32 v99, v99
	v_rcp_f32_e32 v84, v78
	v_rcp_f32_e32 v85, v79
	v_pk_add_f32 v[88:89], v[88:89], 1.0 op_sel_hi:[1,0]
	v_pk_add_f32 v[96:97], v[96:97], 1.0 op_sel_hi:[1,0]
	v_rcp_f32_e32 v92, v88
	v_rcp_f32_e32 v93, v89
	v_pk_add_f32 v[88:89], v[90:91], 1.0 op_sel_hi:[1,0]
	v_pk_mul_f32 v[78:79], v[74:75], v[76:77]
	v_rcp_f32_e32 v94, v88
	v_rcp_f32_e32 v95, v89
	v_pk_fma_f32 v[82:83], v[86:87], v[82:83], v[66:67]
	v_rcp_f32_e32 v100, v96
	v_rcp_f32_e32 v101, v97
	v_pk_add_f32 v[96:97], v[98:99], 1.0 op_sel_hi:[1,0]
	v_pk_mul_f32 v[80:81], v[78:79], v[82:83]
	v_pk_fma_f32 v[84:85], v[86:87], v[84:85], v[66:67]
	v_rcp_f32_e32 v102, v96
	v_rcp_f32_e32 v103, v97
	v_pk_mul_f32 v[88:89], v[80:81], v[84:85]
	v_pk_fma_f32 v[92:93], v[86:87], v[92:93], v[66:67]
	v_pk_fma_f32 v[94:95], v[86:87], v[94:95], v[66:67]
	v_pk_mul_f32 v[90:91], v[88:89], v[92:93]
	v_pk_fma_f32 v[100:101], v[86:87], v[100:101], v[66:67]
	v_pk_mul_f32 v[96:97], v[90:91], v[94:95]
	s_lshl_b32 s0, s70, 9
	v_pk_mul_f32 v[98:99], v[96:97], v[100:101]
	v_pk_fma_f32 v[66:67], v[86:87], v[102:103], v[66:67]
	s_add_i32 s0, s74, s0
	v_lshlrev_b32_e32 v161, 3, v161
	v_pk_mul_f32 v[102:103], v[98:99], v[66:67]
	v_add_u32_e32 v86, s0, v161
	ds_write_b64 v86, v[102:103]
	s_waitcnt vmcnt(4)
	v_cvt_pk_f32_fp8_e32 v[86:87], v104
	v_cvt_pk_f32_fp8_e32 v[164:165], v105
	v_cvt_pk_f32_fp8_sdwa v[162:163], v104 src0_sel:WORD_1
	v_cvt_pk_f32_fp8_sdwa v[104:105], v105 src0_sel:WORD_1
	v_cvt_pk_bf16_f32 v182, v86, v87
	v_cvt_pk_bf16_f32 v184, v164, v165
	v_cvt_pk_f32_fp8_e32 v[86:87], v106
	v_cvt_pk_f32_fp8_e32 v[164:165], v107
	v_cvt_pk_f32_fp8_sdwa v[186:187], v107 src0_sel:WORD_1
	v_cvt_pk_bf16_f32 v183, v162, v163
	v_cvt_pk_f32_fp8_sdwa v[162:163], v106 src0_sel:WORD_1
	v_cvt_pk_bf16_f32 v185, v104, v105
	v_cvt_pk_bf16_f32 v104, v86, v87
	v_cvt_pk_bf16_f32 v106, v164, v165
	v_cvt_pk_bf16_f32 v107, v186, v187
	s_waitcnt vmcnt(4)
	v_cvt_pk_f32_fp8_e32 v[86:87], v108
	s_waitcnt lgkmcnt(0)
	s_barrier
	v_cvt_pk_bf16_f32 v105, v162, v163
	ds_write_b128 v140, v[182:185]
	ds_write_b128 v140, v[104:107] offset:16
	v_cvt_pk_f32_fp8_sdwa v[106:107], v108 src0_sel:WORD_1
	v_cvt_pk_f32_fp8_e32 v[162:163], v109
	v_cvt_pk_f32_fp8_sdwa v[108:109], v109 src0_sel:WORD_1
	v_cvt_pk_bf16_f32 v104, v86, v87
	v_cvt_pk_f32_fp8_e32 v[86:87], v110
	v_cvt_pk_bf16_f32 v105, v106, v107
	v_cvt_pk_bf16_f32 v106, v162, v163
	v_cvt_pk_f32_fp8_sdwa v[162:163], v110 src0_sel:WORD_1
	v_cvt_pk_f32_fp8_e32 v[164:165], v111
	v_cvt_pk_f32_fp8_sdwa v[182:183], v111 src0_sel:WORD_1
	v_cvt_pk_bf16_f32 v107, v108, v109
	v_cvt_pk_bf16_f32 v108, v86, v87
	v_add_u32_e32 v86, 0, v161
	v_cvt_pk_bf16_f32 v109, v162, v163
	v_cvt_pk_bf16_f32 v110, v164, v165
	v_cvt_pk_bf16_f32 v111, v182, v183
	ds_write_b128 v141, v[104:107]
	ds_write_b128 v141, v[108:111] offset:16
	v_add_u32_e32 v87, 0x14600, v86
	v_add_u32_e32 v106, 0x14400, v86
	v_add_u32_e32 v108, 0x14200, v86
	v_add_u32_e32 v86, 0x14000, v86
	ds_read_b64 v[104:105], v87
	ds_read_b64 v[106:107], v106
	ds_read_b64 v[108:109], v108
	ds_read_b64 v[110:111], v86
	s_sub_i32 s60, 7, s70
	s_and_b32 s1, s60, 3
	s_and_b32 s0, s60, 0x1fffffc
	s_cmp_eq_u32 s1, 0
	v_add_u32_e32 v182, s74, v161
	s_cbranch_scc1 .LBB0_565
	s_lshl_b32 s61, s0, 9
	v_subrev_u32_e32 v86, s61, v182
	ds_read_b64 v[86:87], v86 offset:3584
	s_cmp_lt_u32 s1, 2
	s_cbranch_scc1 .LBB0_524

; #define LAS __attribute__((address_space(3)))
; #define BAR_LDS() do { asm volatile("s_waitcnt lgkmcnt(0)" ::: "memory"); __builtin_amdgcn_s_barrier(); asm volatile("" ::: "memory"); } while (0)
; __device__ __forceinline__ float bf2f(unsigned h) { return __uint_as_float(h << 16); }
; __device__ __forceinline__ unsigned pk2(float lo, float hi) { return pg8::cvt_pk_bf16(lo, hi); }
; __device__ __forceinline__ void ret_out_item(const Ctx& X, const bf16* H, bf16* Y, int l, int it, RetOutRegs& R, bool has_next) {
;     ...
;         const float rstd = __builtin_amdgcn_rsqf((red[(ps * 8 + X.wave) * 16 + fr] + red[(ps * 8 + (X.wave ^ 4)) * 16 + fr]) * (1.0f / 128.0f) + EPS);
; #pragma unroll
;         for (int t = 0; t < 4; ++t) { const int v = 64 * vh + 16 * t + 4 * fq; const f32x4 g4 = *(const f32x4*)(gn + v);
;             const float g0 = bf2f(gw[ps][t].x & 0xffffu), g1 = bf2f(gw[ps][t].x >> 16), g2 = bf2f(gw[ps][t].y & 0xffffu), g3 = bf2f(gw[ps][t].y >> 16);
;             const float y0 = (o[t][0] - mu) * rstd * g4.x * (g0 * __builtin_amdgcn_rcpf(1.0f + __expf(-g0))), y1 = (o[t][1] - mu) * rstd * g4.y * (g1 * __builtin_amdgcn_rcpf(1.0f + __expf(-g1)));
;             const float y2 = (o[t][2] - mu) * rstd * g4.z * (g2 * __builtin_amdgcn_rcpf(1.0f + __expf(-g2))), y3 = (o[t][3] - mu) * rstd * g4.w * (g3 * __builtin_amdgcn_rcpf(1.0f + __expf(-g3)));
;             v2u w; w.x = pk2(y0, y1); w.y = pk2(y2, y3); *(LAS v2u*)(AM + tok * 272 + v * 2) = w; } }
;     BAR_LDS();
; #pragma unroll
;     for (int p = 0; p < 4; ++p) { const int idx = X.tid + NTHR * p, row = idx >> 4, c8 = idx & 15; *(v4u*)(Y + (m0 + row) * D + ycol + 8 * c8) = *(const LAS v4u*)(AM + row * 272 + c8 * 16); }
;     BAR_LDS();
.LBB0_568:
	s_or_b64 exec, exec, s[0:1]
	s_waitcnt lgkmcnt(0)
	s_barrier
	ds_read_b32 v40, v153 offset:512
	s_waitcnt lgkmcnt(1)
	ds_read_b32 v41, v172 offset:512
	s_waitcnt vmcnt(3)
	v_mov_b32_e32 v52, v244
	v_mov_b32_e32 v53, v245
	v_mov_b32_e32 v54, v246
	v_mov_b32_e32 v55, v247
	v_lshlrev_b32_e32 v56, 16, v138
	v_and_b32_e32 v57, 0xffff0000, v138
	s_lshl_b64 s[0:1], s[22:23], 1
	s_waitcnt lgkmcnt(0)
	v_add_f32_e32 v40, v40, v41
	v_mul_f32_e32 v41, 0xbfb8aa3b, v56
	v_fmamk_f32 v40, v40, 0x3c000000, v1
	v_exp_f32_e32 v41, v41
	v_rsq_f32_e32 v40, v40
	s_add_u32 s0, s28, s0
	s_addc_u32 s1, s29, s1
	v_add_f32_e32 v41, 1.0, v41
	v_rcp_f32_e32 v58, v41
	v_pk_mul_f32 v[50:51], v[50:51], v[40:41] op_sel_hi:[1,0]
	v_mul_f32_e32 v41, 0xbfb8aa3b, v57
	v_exp_f32_e32 v41, v41
	s_andn2_b64 vcc, exec, s[18:19]
	v_add_f32_e32 v41, 1.0, v41
	v_rcp_f32_e32 v59, v41
	s_waitcnt vmcnt(3)
	v_pk_mul_f32 v[50:51], v[52:53], v[50:51]
	v_pk_mul_f32 v[52:53], v[58:59], v[56:57]
	s_nop 0
	v_pk_mul_f32 v[50:51], v[52:53], v[50:51]
	v_lshlrev_b32_e32 v52, 16, v139
	v_mul_f32_e32 v41, 0xbfb8aa3b, v52
	v_exp_f32_e32 v41, v41
	v_and_b32_e32 v53, 0xffff0000, v139
	v_cvt_pk_bf16_f32 v50, v50, v51
	v_add_f32_e32 v41, 1.0, v41
	v_rcp_f32_e32 v56, v41
	v_pk_mul_f32 v[48:49], v[48:49], v[40:41] op_sel_hi:[1,0]
	v_mul_f32_e32 v41, 0xbfb8aa3b, v53
	v_exp_f32_e32 v41, v41
	v_pk_mul_f32 v[48:49], v[54:55], v[48:49]
	v_add_f32_e32 v41, 1.0, v41
	v_rcp_f32_e32 v57, v41
	v_add_u32_e32 v41, v189, v185
	v_pk_mul_f32 v[52:53], v[56:57], v[52:53]
	s_nop 0
	v_pk_mul_f32 v[48:49], v[52:53], v[48:49]
	v_lshlrev_b32_e32 v52, 16, v136
	v_cvt_pk_bf16_f32 v51, v48, v49
	ds_write_b64 v41, v[50:51]
	v_mul_f32_e32 v41, 0xbfb8aa3b, v52
	v_exp_f32_e32 v41, v41
	v_and_b32_e32 v53, 0xffff0000, v136
	v_add_f32_e32 v41, 1.0, v41
	v_rcp_f32_e32 v54, v41
	v_pk_mul_f32 v[46:47], v[46:47], v[40:41] op_sel_hi:[1,0]
	v_mul_f32_e32 v41, 0xbfb8aa3b, v53
	v_exp_f32_e32 v41, v41
	s_waitcnt vmcnt(2)
	v_pk_mul_f32 v[46:47], v[232:233], v[46:47]
	v_add_f32_e32 v41, 1.0, v41
	v_rcp_f32_e32 v55, v41
	s_nop 0
	v_pk_mul_f32 v[48:49], v[54:55], v[52:53]
	s_nop 0
	v_pk_mul_f32 v[46:47], v[48:49], v[46:47]
	v_lshlrev_b32_e32 v48, 16, v137
	v_mul_f32_e32 v41, 0xbfb8aa3b, v48
	v_exp_f32_e32 v41, v41
	v_and_b32_e32 v49, 0xffff0000, v137
	v_cvt_pk_bf16_f32 v46, v46, v47
	v_add_f32_e32 v41, 1.0, v41
	v_rcp_f32_e32 v52, v41
	v_pk_mul_f32 v[44:45], v[44:45], v[40:41] op_sel_hi:[1,0]
	v_mul_f32_e32 v41, 0xbfb8aa3b, v49
	v_exp_f32_e32 v41, v41
	v_pk_mul_f32 v[44:45], v[234:235], v[44:45]
	v_add_f32_e32 v41, 1.0, v41
	v_rcp_f32_e32 v53, v41
	v_add_u32_e32 v41, v189, v186
	v_pk_mul_f32 v[48:49], v[52:53], v[48:49]
	s_nop 0
	v_pk_mul_f32 v[44:45], v[48:49], v[44:45]
	v_lshlrev_b32_e32 v48, 16, v134
	v_cvt_pk_bf16_f32 v47, v44, v45
	ds_write_b64 v41, v[46:47]
	v_mul_f32_e32 v41, 0xbfb8aa3b, v48
	v_exp_f32_e32 v41, v41
	v_and_b32_e32 v49, 0xffff0000, v134
	v_add_f32_e32 v41, 1.0, v41
	v_rcp_f32_e32 v50, v41
	v_pk_mul_f32 v[36:37], v[36:37], v[40:41] op_sel_hi:[1,0]
	v_mul_f32_e32 v41, 0xbfb8aa3b, v49
	v_exp_f32_e32 v41, v41
	s_waitcnt vmcnt(1)
	v_pk_mul_f32 v[36:37], v[36:37], v[236:237]
	v_add_f32_e32 v41, 1.0, v41
	v_rcp_f32_e32 v51, v41
	s_nop 0
	v_pk_mul_f32 v[44:45], v[50:51], v[48:49]
	s_nop 0
	v_pk_mul_f32 v[36:37], v[44:45], v[36:37]
	v_lshlrev_b32_e32 v44, 16, v135
	v_mul_f32_e32 v41, 0xbfb8aa3b, v44
	v_exp_f32_e32 v41, v41
	v_and_b32_e32 v45, 0xffff0000, v135
	v_cvt_pk_bf16_f32 v36, v36, v37
	v_add_f32_e32 v41, 1.0, v41
	v_rcp_f32_e32 v48, v41
	v_pk_mul_f32 v[34:35], v[34:35], v[40:41] op_sel_hi:[1,0]
	v_mul_f32_e32 v41, 0xbfb8aa3b, v45
	v_exp_f32_e32 v41, v41
	v_pk_mul_f32 v[34:35], v[34:35], v[238:239]
	v_add_f32_e32 v41, 1.0, v41
	v_rcp_f32_e32 v49, v41
	s_nop 0
	v_pk_mul_f32 v[44:45], v[48:49], v[44:45]
	s_nop 0
	v_pk_mul_f32 v[34:35], v[44:45], v[34:35]
	v_lshlrev_b32_e32 v44, 16, v132
	v_cvt_pk_bf16_f32 v37, v34, v35
	v_add_u32_e32 v34, v189, v187
	ds_write_b64 v34, v[36:37]
	v_mul_f32_e32 v41, 0xbfb8aa3b, v44
	v_exp_f32_e32 v41, v41
	v_and_b32_e32 v45, 0xffff0000, v132
	v_add_f32_e32 v41, 1.0, v41
	v_rcp_f32_e32 v46, v41
	v_pk_mul_f32 v[42:43], v[42:43], v[40:41] op_sel_hi:[1,0]
	v_mul_f32_e32 v41, 0xbfb8aa3b, v45
	v_exp_f32_e32 v41, v41
	s_waitcnt vmcnt(0)
	v_pk_mul_f32 v[34:35], v[42:43], v[240:241]
	v_add_f32_e32 v41, 1.0, v41
	v_rcp_f32_e32 v47, v41
	s_nop 0
	v_pk_mul_f32 v[42:43], v[46:47], v[44:45]
	s_nop 0
	v_pk_mul_f32 v[34:35], v[42:43], v[34:35]
	v_lshlrev_b32_e32 v42, 16, v133
	v_mul_f32_e32 v41, 0xbfb8aa3b, v42
	v_exp_f32_e32 v41, v41
	v_and_b32_e32 v43, 0xffff0000, v133
	v_cvt_pk_bf16_f32 v34, v34, v35
	v_add_f32_e32 v41, 1.0, v41
	v_pk_mul_f32 v[38:39], v[38:39], v[40:41] op_sel_hi:[1,0]
	v_rcp_f32_e32 v44, v41
	v_pk_mul_f32 v[36:37], v[38:39], v[242:243]
	v_mul_f32_e32 v38, 0xbfb8aa3b, v43
	v_exp_f32_e32 v38, v38
	s_nop 0
	v_add_f32_e32 v38, 1.0, v38
	v_rcp_f32_e32 v45, v38
	s_nop 0
	v_pk_mul_f32 v[38:39], v[44:45], v[42:43]
	s_nop 0
	v_pk_mul_f32 v[36:37], v[38:39], v[36:37]
	v_lshl_add_u64 v[38:39], s[12:13], 0, v[106:107]
	v_cvt_pk_bf16_f32 v35, v36, v37
	v_add_u32_e32 v36, v189, v188
	ds_write_b64 v36, v[34:35]
	s_waitcnt lgkmcnt(0)
	s_barrier
	ds_read_b128 v[34:37], v210
	v_lshlrev_b64 v[38:39], 12, v[38:39]
	v_lshl_add_u64 v[38:39], s[0:1], 0, v[38:39]
	v_lshl_add_u64 v[38:39], v[38:39], 0, v[158:159]
	s_waitcnt lgkmcnt(0)
	global_store_dwordx4 v[38:39], v[34:37], off offset:1536
	ds_read_b128 v[34:37], v211
	v_lshl_add_u64 v[38:39], s[12:13], 0, v[108:109]
	v_lshlrev_b64 v[38:39], 12, v[38:39]
	v_lshl_add_u64 v[38:39], s[0:1], 0, v[38:39]
	v_lshl_add_u64 v[38:39], v[38:39], 0, v[158:159]
	s_waitcnt lgkmcnt(0)
	global_store_dwordx4 v[38:39], v[34:37], off offset:1536
	ds_read_b128 v[34:37], v212
	v_lshl_add_u64 v[38:39], s[12:13], 0, v[110:111]
	v_lshlrev_b64 v[38:39], 12, v[38:39]
	v_lshl_add_u64 v[38:39], s[0:1], 0, v[38:39]
	v_lshl_add_u64 v[38:39], v[38:39], 0, v[158:159]
	s_waitcnt lgkmcnt(0)
	global_store_dwordx4 v[38:39], v[34:37], off offset:1536
	ds_read_b128 v[34:37], v213
	v_lshl_add_u64 v[38:39], s[12:13], 0, v[112:113]
	v_lshlrev_b64 v[38:39], 12, v[38:39]
	v_lshl_add_u64 v[38:39], s[0:1], 0, v[38:39]
	v_lshl_add_u64 v[38:39], v[38:39], 0, v[158:159]
	s_waitcnt lgkmcnt(0)
	global_store_dwordx4 v[38:39], v[34:37], off offset:1536
	s_waitcnt lgkmcnt(0)
	s_barrier
	s_mov_b32 s0, s38
	s_cbranch_vccz .LBB0_597

; #define LAS __attribute__((address_space(3)))
; __device__ __forceinline__ float bf2f(unsigned h) { return __uint_as_float(h << 16); }
; __device__ __forceinline__ unsigned pk2(float lo, float hi) { return pg8::cvt_pk_bf16(lo, hi); }
; #define MFMA16(a, b, c) __builtin_amdgcn_mfma_f32_16x16x32_bf16((a), (b), (c), 0, 0, 0)
; __device__ __forceinline__ void ret_out_item(const Ctx& X, const bf16* H, bf16* Y, int l, int it, RetOutRegs& R, bool has_next) {
;     ...
;         for (int ks = 0; ks < 4; ++ks) { const bf16x8 bb = ldsfrag(AM, tok, 272, 32 * ks + 8 * fq);
; #pragma unroll
;             for (int vt = 0; vt < 4; ++vt) { const bf16x8 a = vtfrag(VT, 64 * vh + 16 * vt + fr, 272, 32 * ks + 8 * fq); o[vt] = MFMA16(a, bb, o[vt]); } }
;     ...
;         const float rstd = __builtin_amdgcn_rsqf((red[(ps * 8 + X.wave) * 16 + fr] + red[(ps * 8 + (X.wave ^ 4)) * 16 + fr]) * (1.0f / 128.0f) + EPS);
; #pragma unroll
;         for (int t = 0; t < 4; ++t) { const int v = 64 * vh + 16 * t + 4 * fq; const f32x4 g4 = *(const f32x4*)(gn + v);
;             const float g0 = bf2f(gw[ps][t].x & 0xffffu), g1 = bf2f(gw[ps][t].x >> 16), g2 = bf2f(gw[ps][t].y & 0xffffu), g3 = bf2f(gw[ps][t].y >> 16);
;             const float y0 = (o[t][0] - mu) * rstd * g4.x * (g0 * __builtin_amdgcn_rcpf(1.0f + __expf(-g0))), y1 = (o[t][1] - mu) * rstd * g4.y * (g1 * __builtin_amdgcn_rcpf(1.0f + __expf(-g1)));
;             const float y2 = (o[t][2] - mu) * rstd * g4.z * (g2 * __builtin_amdgcn_rcpf(1.0f + __expf(-g2))), y3 = (o[t][3] - mu) * rstd * g4.w * (g3 * __builtin_amdgcn_rcpf(1.0f + __expf(-g3)));
;             v2u w; w.x = pk2(y0, y1); w.y = pk2(y2, y3); *(LAS v2u*)(AM + tok * 272 + v * 2) = w; } }
.LBB0_593:
	s_or_b64 exec, exec, s[24:25]
	s_ashr_i32 s23, s22, 31
	s_waitcnt lgkmcnt(0)
	s_barrier
	v_add_u32_e32 v153, s36, v174
	v_add_u32_e32 v172, s37, v174
	s_add_u32 s24, s0, s16
	ds_read_b32 v152, v153
	ds_read_b32 v162, v172
	s_addc_u32 s25, s1, s17
	s_lshl_b64 s[0:1], s[22:23], 2
	s_add_u32 s0, s24, s0
	s_addc_u32 s1, s25, s1
	s_waitcnt lgkmcnt(2)
	v_lshl_add_u64 v[140:141], v[114:115], 2, s[0:1]
	s_waitcnt lgkmcnt(0)
	v_add_f32_e32 v152, v152, v162
	global_load_dwordx4 v[162:165], v[140:141], off
	global_load_dwordx4 v[236:239], v[140:141], off offset:64
	global_load_dwordx4 v[240:243], v[140:141], off offset:128
	global_load_dwordx4 v[244:247], v[140:141], off offset:192
	s_waitcnt vmcnt(8)
	v_lshlrev_b32_e32 v232, 16, v154
	v_and_b32_e32 v233, 0xffff0000, v154
	v_mul_f32_e32 v154, 0xbfb8aa3b, v232
	v_exp_f32_e32 v154, v154
	v_fmamk_f32 v152, v152, 0x3c000000, v1
	v_rsq_f32_e32 v152, v152
	v_mul_f32_e32 v121, v121, v191
	v_add_f32_e32 v154, 1.0, v154
	v_rcp_f32_e32 v234, v154
	v_mul_f32_e32 v154, 0xbfb8aa3b, v233
	v_exp_f32_e32 v154, v154
	v_pk_mul_f32 v[170:171], v[170:171], v[152:153] op_sel_hi:[1,0]
	v_pk_mul_f32 v[168:169], v[168:169], v[152:153] op_sel_hi:[1,0]
	v_pk_mul_f32 v[166:167], v[166:167], v[152:153] op_sel_hi:[1,0]
	v_add_f32_e32 v154, 1.0, v154
	v_rcp_f32_e32 v235, v154
	v_lshlrev_b32_e32 v154, 16, v155
	v_and_b32_e32 v155, 0xffff0000, v155
	v_pk_mul_f32 v[156:157], v[156:157], v[152:153] op_sel_hi:[1,0]
	v_pk_mul_f32 v[100:101], v[100:101], v[152:153] op_sel_hi:[1,0]
	v_pk_mul_f32 v[98:99], v[98:99], v[152:153] op_sel_hi:[1,0]
	v_pk_mul_f32 v[150:151], v[150:151], v[152:153] op_sel_hi:[1,0]
	s_waitcnt vmcnt(3)
	v_pk_mul_f32 v[162:163], v[162:163], v[170:171]
	v_pk_mul_f32 v[170:171], v[234:235], v[232:233]
	v_pk_mul_f32 v[164:165], v[164:165], v[168:169]
	v_pk_mul_f32 v[162:163], v[170:171], v[162:163]
	v_mul_f32_e32 v170, 0xbfb8aa3b, v154
	v_mul_f32_e32 v168, 0xbfb8aa3b, v155
	v_exp_f32_e32 v170, v170
	v_exp_f32_e32 v168, v168
	v_cvt_pk_bf16_f32 v162, v162, v163
	v_add_f32_e32 v170, 1.0, v170
	v_add_f32_e32 v168, 1.0, v168
	v_rcp_f32_e32 v170, v170
	v_rcp_f32_e32 v171, v168
	s_nop 0
	v_pk_mul_f32 v[154:155], v[170:171], v[154:155]
	s_nop 0
	v_pk_mul_f32 v[154:155], v[154:155], v[164:165]
	s_nop 0
	v_cvt_pk_bf16_f32 v163, v154, v155
	v_add_u32_e32 v154, v175, v185
	ds_write_b64 v154, v[162:163]
	v_lshlrev_b32_e32 v154, 16, v146
	v_and_b32_e32 v155, 0xffff0000, v146
	v_mul_f32_e32 v146, 0xbfb8aa3b, v154
	v_exp_f32_e32 v146, v146
	s_waitcnt vmcnt(2)
	v_pk_mul_f32 v[162:163], v[236:237], v[166:167]
	v_add_f32_e32 v146, 1.0, v146
	v_rcp_f32_e32 v168, v146
	v_mul_f32_e32 v146, 0xbfb8aa3b, v155
	v_exp_f32_e32 v146, v146
	v_pk_mul_f32 v[156:157], v[238:239], v[156:157]
	v_add_f32_e32 v146, 1.0, v146
	v_rcp_f32_e32 v169, v146
	v_lshlrev_b32_e32 v146, 16, v147
	v_and_b32_e32 v147, 0xffff0000, v147
	v_pk_mul_f32 v[154:155], v[168:169], v[154:155]
	s_nop 0
	v_pk_mul_f32 v[154:155], v[154:155], v[162:163]
	v_mul_f32_e32 v162, 0xbfb8aa3b, v146
	v_mul_f32_e32 v163, 0xbfb8aa3b, v147
	v_exp_f32_e32 v162, v162
	v_exp_f32_e32 v163, v163
	v_cvt_pk_bf16_f32 v154, v154, v155
	v_add_f32_e32 v162, 1.0, v162
	v_add_f32_e32 v163, 1.0, v163
	v_rcp_f32_e32 v162, v162
	v_rcp_f32_e32 v163, v163
	s_nop 0
	v_pk_mul_f32 v[146:147], v[162:163], v[146:147]
	s_nop 0
	v_pk_mul_f32 v[146:147], v[146:147], v[156:157]
	s_nop 0
	v_cvt_pk_bf16_f32 v155, v146, v147
	v_add_u32_e32 v146, v175, v186
	ds_write_b64 v146, v[154:155]
	v_lshlrev_b32_e32 v146, 16, v144
	v_and_b32_e32 v147, 0xffff0000, v144
	v_mul_f32_e32 v144, 0xbfb8aa3b, v146
	v_exp_f32_e32 v144, v144
	s_waitcnt vmcnt(1)
	v_pk_mul_f32 v[100:101], v[100:101], v[240:241]
	v_add_f32_e32 v144, 1.0, v144
	v_rcp_f32_e32 v162, v144
	v_mul_f32_e32 v144, 0xbfb8aa3b, v147
	v_exp_f32_e32 v144, v144
	v_pk_mul_f32 v[98:99], v[98:99], v[242:243]
	v_add_f32_e32 v144, 1.0, v144
	v_rcp_f32_e32 v163, v144
	v_lshlrev_b32_e32 v144, 16, v145
	v_and_b32_e32 v145, 0xffff0000, v145
	v_pk_mul_f32 v[146:147], v[162:163], v[146:147]
	s_nop 0
	v_pk_mul_f32 v[100:101], v[146:147], v[100:101]
	v_mul_f32_e32 v146, 0xbfb8aa3b, v144
	v_mul_f32_e32 v147, 0xbfb8aa3b, v145
	v_exp_f32_e32 v146, v146
	v_exp_f32_e32 v147, v147
	v_cvt_pk_bf16_f32 v100, v100, v101
	v_add_f32_e32 v146, 1.0, v146
	v_add_f32_e32 v147, 1.0, v147
	v_rcp_f32_e32 v146, v146
	v_rcp_f32_e32 v147, v147
	s_nop 0
	v_pk_mul_f32 v[144:145], v[146:147], v[144:145]
	s_nop 0
	v_pk_mul_f32 v[98:99], v[144:145], v[98:99]
	v_lshlrev_b32_e32 v144, 16, v142
	v_cvt_pk_bf16_f32 v101, v98, v99
	v_add_u32_e32 v98, v175, v187
	ds_write_b64 v98, v[100:101]
	v_and_b32_e32 v145, 0xffff0000, v142
	v_mul_f32_e32 v142, 0xbfb8aa3b, v144
	v_exp_f32_e32 v142, v142
	s_waitcnt vmcnt(0)
	v_pk_mul_f32 v[98:99], v[150:151], v[244:245]
	v_add_f32_e32 v142, 1.0, v142
	v_rcp_f32_e32 v146, v142
	v_mul_f32_e32 v142, 0xbfb8aa3b, v145
	v_exp_f32_e32 v142, v142
	v_add_u32_e32 v150, v189, v176
	v_add_f32_e32 v142, 1.0, v142
	v_rcp_f32_e32 v147, v142
	v_lshlrev_b32_e32 v142, 16, v143
	v_and_b32_e32 v143, 0xffff0000, v143
	v_pk_mul_f32 v[144:145], v[146:147], v[144:145]
	s_nop 0
	v_pk_mul_f32 v[98:99], v[144:145], v[98:99]
	v_mul_f32_e32 v144, 0xbfb8aa3b, v142
	v_mul_f32_e32 v145, 0xbfb8aa3b, v143
	v_exp_f32_e32 v144, v144
	v_exp_f32_e32 v145, v145
	v_pk_mul_f32 v[146:147], v[148:149], v[152:153] op_sel_hi:[1,0]
	v_cvt_pk_bf16_f32 v98, v98, v99
	v_add_f32_e32 v144, 1.0, v144
	v_add_f32_e32 v145, 1.0, v145
	v_rcp_f32_e32 v144, v144
	v_rcp_f32_e32 v145, v145
	v_pk_mul_f32 v[100:101], v[146:147], v[246:247]
	v_pk_mul_f32 v[142:143], v[144:145], v[142:143]
	s_nop 0
	v_pk_mul_f32 v[100:101], v[142:143], v[100:101]
	s_nop 0
	v_cvt_pk_bf16_f32 v99, v100, v101
	v_add_u32_e32 v100, v175, v188
	ds_write_b64 v100, v[98:99]
	global_load_dwordx4 v[244:247], v[140:141], off
	global_load_dwordx4 v[232:235], v[140:141], off offset:64
	global_load_dwordx4 v[236:239], v[140:141], off offset:128
	global_load_dwordx4 v[240:243], v[140:141], off offset:192
	v_add_u32_e32 v98, v189, v119
	ds_read_b128 v[98:101], v98
	ds_read_b128 v[142:145], v214 offset:36864
	ds_read_b128 v[146:149], v215 offset:36864
	ds_read_b128 v[154:157], v216 offset:36864
	ds_read_b128 v[162:165], v217 offset:36864
	s_waitcnt lgkmcnt(3)
; #define MFMA16(a, b, c) __builtin_amdgcn_mfma_f32_16x16x32_bf16((a), (b), (c), 0, 0, 0)
; __device__ __forceinline__ void ret_out_item(const Ctx& X, const bf16* H, bf16* Y, int l, int it, RetOutRegs& R, bool has_next) {
;     ...
;         for (int ks = 0; ks < 4; ++ks) { const bf16x8 bb = ldsfrag(AM, tok, 272, 32 * ks + 8 * fq);
; #pragma unroll
;             for (int vt = 0; vt < 4; ++vt) { const bf16x8 a = vtfrag(VT, 64 * vh + 16 * vt + fr, 272, 32 * ks + 8 * fq); o[vt] = MFMA16(a, bb, o[vt]); } }
;         const bf16x8 bq0 = ldsfrag(Q, tok, 144, 8 * fq), bq1 = ldsfrag(Q, tok, 144, 32 + 8 * fq);
;         const float cf = __builtin_amdgcn_exp2f((float)(tok + 1) * l2f), cb = __builtin_amdgcn_exp2f((float)(RCH - tok) * l2b);
;         {
;             f32x4 tf[4];
; #pragma unroll
;             for (int vt = 0; vt < 4; ++vt) { tf[vt] = MFMA16(sff[0][vt], bq0, ((f32x4){0.f, 0.f, 0.f, 0.f})); tf[vt] = MFMA16(sff[1][vt], bq1, tf[vt]); }
; #pragma unroll
;             for (int t = 0; t < 4; ++t) o[t] = o[t] + tf[t] * cf;
; #pragma unroll
;             for (int vt = 0; vt < 4; ++vt) { tf[vt] = MFMA16(sfb[0][vt], bq0, ((f32x4){0.f, 0.f, 0.f, 0.f})); tf[vt] = MFMA16(sfb[1][vt], bq1, tf[vt]); }
; #pragma unroll
;             for (int t = 0; t < 4; ++t) o[t] = o[t] + tf[t] * cb;
;         }
;         float s_ = 0.f;
; #pragma unroll
;         for (int t = 0; t < 4; ++t) s_ += (o[t][0] + o[t][1]) + (o[t][2] + o[t][3]);
;         s_ += __shfl_xor(s_, 16); s_ += __shfl_xor(s_, 32);
;         if (fq == 0) red[512 + (ps * 8 + X.wave) * 16 + fr] = s_;
	v_mfma_f32_16x16x32_bf16 v[142:145], v[142:145], v[98:101], 0
	s_waitcnt lgkmcnt(2)
	v_mfma_f32_16x16x32_bf16 v[146:149], v[146:149], v[98:101], 0
	s_waitcnt lgkmcnt(1)
	v_mfma_f32_16x16x32_bf16 v[154:157], v[154:157], v[98:101], 0
	s_waitcnt lgkmcnt(0)
	v_mfma_f32_16x16x32_bf16 v[98:101], v[162:165], v[98:101], 0
	ds_read_b128 v[162:165], v150
	ds_read_b128 v[166:169], v218 offset:36864
	v_add_u32_e32 v150, v189, v177
	s_waitcnt lgkmcnt(0)
	v_mfma_f32_16x16x32_bf16 v[142:145], v[166:169], v[162:165], v[142:145]
	ds_read_b128 v[166:169], v219 offset:36864
	s_waitcnt lgkmcnt(0)
	v_mfma_f32_16x16x32_bf16 v[146:149], v[166:169], v[162:165], v[146:149]
	ds_read_b128 v[166:169], v220 offset:36864
	s_waitcnt lgkmcnt(0)
	v_mfma_f32_16x16x32_bf16 v[154:157], v[166:169], v[162:165], v[154:157]
	ds_read_b128 v[166:169], v221 offset:36864
	s_waitcnt lgkmcnt(0)
	v_mfma_f32_16x16x32_bf16 v[98:101], v[166:169], v[162:165], v[98:101]
	ds_read_b128 v[162:165], v150
	ds_read_b128 v[166:169], v222 offset:36864
	v_add_u32_e32 v150, v189, v178
	s_waitcnt lgkmcnt(0)
	v_mfma_f32_16x16x32_bf16 v[142:145], v[166:169], v[162:165], v[142:145]
	ds_read_b128 v[166:169], v223 offset:36864
	s_waitcnt lgkmcnt(0)
	v_mfma_f32_16x16x32_bf16 v[146:149], v[166:169], v[162:165], v[146:149]
	ds_read_b128 v[166:169], v224 offset:36864
	s_waitcnt lgkmcnt(0)
	v_mfma_f32_16x16x32_bf16 v[154:157], v[166:169], v[162:165], v[154:157]
	ds_read_b128 v[166:169], v225 offset:36864
	s_waitcnt lgkmcnt(0)
	v_mfma_f32_16x16x32_bf16 v[98:101], v[166:169], v[162:165], v[98:101]
	ds_read_b128 v[162:165], v150
	ds_read_b128 v[166:169], v226 offset:36864
	v_mul_f32_e32 v150, v230, v190
	s_waitcnt lgkmcnt(0)
	v_mfma_f32_16x16x32_bf16 v[142:145], v[166:169], v[162:165], v[142:145]
	ds_read_b128 v[166:169], v227 offset:36864
	s_waitcnt lgkmcnt(0)
	v_mfma_f32_16x16x32_bf16 v[146:149], v[166:169], v[162:165], v[146:149]
	ds_read_b128 v[166:169], v228 offset:36864
	s_waitcnt lgkmcnt(0)
	v_mfma_f32_16x16x32_bf16 v[154:157], v[166:169], v[162:165], v[154:157]
	ds_read_b128 v[166:169], v229 offset:36864
	s_waitcnt lgkmcnt(0)
	v_mfma_f32_16x16x32_bf16 v[98:101], v[166:169], v[162:165], v[98:101]
	ds_read_b128 v[162:165], v209
	ds_read_b128 v[166:169], v209 offset:64
	s_waitcnt lgkmcnt(1)
	v_mfma_f32_16x16x32_bf16 v[66:69], v[66:69], v[162:165], 0
	v_mfma_f32_16x16x32_bf16 v[70:73], v[70:73], v[162:165], 0
	v_mfma_f32_16x16x32_bf16 v[78:81], v[78:81], v[162:165], 0
	v_mfma_f32_16x16x32_bf16 v[38:41], v[38:41], v[162:165], 0
	v_mfma_f32_16x16x32_bf16 v[46:49], v[46:49], v[162:165], 0
	v_mfma_f32_16x16x32_bf16 v[34:37], v[34:37], v[162:165], 0
	v_mfma_f32_16x16x32_bf16 v[74:77], v[74:77], v[162:165], 0
	s_waitcnt lgkmcnt(0)
	v_mfma_f32_16x16x32_bf16 v[66:69], v[82:85], v[166:169], v[66:69]
	v_exp_f32_e32 v82, v150
	v_mfma_f32_16x16x32_bf16 v[42:45], v[42:45], v[162:165], 0
	v_mfma_f32_16x16x32_bf16 v[70:73], v[86:89], v[166:169], v[70:73]
	s_nop 4
	v_fma_f32 v68, v82, v68, v144
	v_fma_f32 v69, v82, v69, v145
	v_pk_fma_f32 v[66:67], v[82:83], v[66:67], v[142:143] op_sel_hi:[0,1,1]
	v_mfma_f32_16x16x32_bf16 v[78:81], v[94:97], v[166:169], v[78:81]
	v_mfma_f32_16x16x32_bf16 v[38:41], v[58:61], v[166:169], v[38:41]
	v_fma_f32 v72, v82, v72, v148
	v_fma_f32 v73, v82, v73, v149
	v_pk_fma_f32 v[70:71], v[82:83], v[70:71], v[146:147] op_sel_hi:[0,1,1]
	s_nop 3
	v_pk_fma_f32 v[78:79], v[82:83], v[78:79], v[98:99] op_sel_hi:[0,1,1]
	v_mfma_f32_16x16x32_bf16 v[58:61], v[62:65], v[166:169], v[46:49]
	v_exp_f32_e32 v62, v121
	v_pk_fma_f32 v[80:81], v[82:83], v[80:81], v[100:101] op_sel_hi:[0,1,1]
	v_mfma_f32_16x16x32_bf16 v[48:51], v[50:53], v[166:169], v[34:37]
	v_fma_f32 v46, v62, v38, v66
	v_fma_f32 v47, v62, v39, v67
	v_mfma_f32_16x16x32_bf16 v[74:77], v[90:93], v[166:169], v[74:77]
	s_nop 1
	v_fma_f32 v36, v62, v60, v72
	v_fma_f32 v37, v62, v61, v73
	s_nop 0
	v_pk_fma_f32 v[38:39], v[62:63], v[50:51], v[80:81] op_sel_hi:[0,1,1]
	v_add_f32_e32 v50, v36, v37
	v_mfma_f32_16x16x32_bf16 v[54:57], v[54:57], v[166:169], v[42:45]
	s_nop 2
	v_fma_f32 v42, v62, v40, v68
	v_fma_f32 v43, v62, v41, v69
	v_pk_fma_f32 v[44:45], v[62:63], v[58:59], v[70:71] op_sel_hi:[0,1,1]
	v_pk_fma_f32 v[40:41], v[62:63], v[48:49], v[78:79] op_sel_hi:[0,1,1]
	v_add_f32_e32 v48, v46, v47
	v_add_f32_e32 v49, v42, v43
	v_pk_fma_f32 v[76:77], v[82:83], v[76:77], v[156:157] op_sel_hi:[0,1,1]
	v_pk_fma_f32 v[74:75], v[82:83], v[74:75], v[154:155] op_sel_hi:[0,1,1]
	v_add_f32_e32 v48, v48, v49
	v_add_f32_e32 v49, v44, v45
	v_pk_fma_f32 v[34:35], v[62:63], v[56:57], v[76:77] op_sel_hi:[0,1,1]
	v_pk_fma_f32 v[52:53], v[62:63], v[54:55], v[74:75] op_sel_hi:[0,1,1]
	v_add_f32_e32 v48, 0, v48
	v_add_f32_e32 v49, v49, v50
	v_add_f32_e32 v48, v48, v49
	v_add_f32_e32 v49, v52, v53
	v_add_f32_e32 v50, v34, v35
	v_add_f32_e32 v49, v49, v50
	v_add_f32_e32 v48, v48, v49
	v_add_f32_e32 v49, v40, v41
	v_add_f32_e32 v50, v38, v39
	v_add_f32_e32 v49, v49, v50
	v_add_f32_e32 v48, v48, v49
	ds_bpermute_b32 v49, v131, v48
	s_waitcnt lgkmcnt(0)
	v_add_f32_e32 v48, v48, v49
	ds_bpermute_b32 v49, v231, v48
	s_and_saveexec_b64 s[0:1], s[40:41]
	s_cbranch_execz .LBB0_595
	s_waitcnt lgkmcnt(0)
	v_add_f32_e32 v48, v48, v49
	ds_write_b32 v192, v48
